# phase 7: chunk_prep tasks re-dealt 7/9 between the waves that also prepare a sample row and the ones that do not, on top of the stacked file
# speedup vs baseline: 1.0002x; 1.0002x over previous
; #define GAS __attribute__((address_space(1)))
; #define LAS __attribute__((address_space(3)))
; DI void chunk_prep(const bf16* PROJ, const float* mu, const bf16* LO, const float* pw0, const float* pa0, const float* pkk, const float* pka, const float* prk, float* SCAL, unsigned char* OPS, float* G15, LAS unsigned char* lds, int gw, int NGW, int wave, int lane) {
;     LAS unsigned char* base = lds + wave * 16384;
;     const int d = lane, x = lane & 15, q = lane >> 4;
;     for (int task = gw; task < NTASK; task += NGW) {
;         const int chain = task / NCHUNK, c = task - chain * NCHUNK, bb = chain >> 3, hd = chain & 7;
;         const size_t m0 = (size_t)bb * SEQ + (size_t)c * 16;
;         float a[16], b[16], k[16], r[16]; float g = 1.f;
;         {
;             const int ch = hd * 64 + d;
;             const float w0v = ((const GAS float*)pw0)[ch], a0v = ((const GAS float*)pa0)[ch], kkv = ((const GAS float*)pkk)[ch], kav = ((const GAS float*)pka)[ch], rkv = ((const GAS float*)prk)[ch];
;             const float mur = ((const GAS float*)mu)[ch], muk = ((const GAS float*)mu)[512 + ch];
;             float w[16], wl[16], al[16];
.LBB0_853:
	s_mov_b32 s100, 0
	v_readlane_b32 s0, v254, 11
	s_movk_i32 s101, 0x4000
	s_cmpk_lt_i32 s0, 0x400
	s_cselect_b32 s101, 0x3800, s101
	s_mov_b64 s[10:11], s[96:97]
	s_mov_b64 s[2:3], s[96:97]
	s_waitcnt lgkmcnt(0)
	s_mov_b64 s[6:7], s[96:97]
	s_mov_b64 s[4:5], s[96:97]
	s_mov_b64 s[8:9], s[96:97]
	s_mov_b64 s[12:13], s[96:97]
	s_cmpk_gt_i32 s0, 0x3fff
	v_readlane_b32 s1, v254, 12
	s_cbranch_scc1 .LBB0_890
	s_add_u32 s20, s44, 0x52400000
	s_addc_u32 s21, s45, 0
	s_waitcnt vmcnt(0)
	v_and_b32_e32 v2, 15, v0
	v_lshrrev_b32_e32 v3, 2, v186
	v_readlane_b32 s16, v254, 11
	s_add_u32 s0, s44, 0x77600000
	v_and_b32_e32 v1, 48, v0
	v_and_b32_e32 v6, 12, v3
	v_lshlrev_b32_e32 v7, 6, v2
	v_lshlrev_b32_e32 v8, 5, v2
	v_readlane_b32 s17, v254, 12
	s_mov_b32 s50, s16
	s_load_dwordx2 s[18:19], s[10:11], 0x90
	s_load_dwordx2 s[22:23], s[2:3], 0x98
	s_load_dwordx2 s[24:25], s[6:7], 0xa8
	s_load_dwordx2 s[26:27], s[4:5], 0xc0
	s_load_dwordx2 s[28:29], s[8:9], 0xc8
	s_load_dwordx2 s[30:31], s[12:13], 0xd0
	s_addc_u32 s1, s45, 0
	v_or_b32_e32 v10, v7, v1
	v_or_b32_e32 v7, v6, v7
	v_lshl_or_b32 v12, v6, 1, v8
	v_cmp_lt_u32_e64 s[4:5], v6, v2
	v_cmp_gt_u32_e64 s[6:7], v6, v2
	v_or_b32_e32 v8, 1, v6
	v_or_b32_e32 v6, 2, v6
	s_ashr_i32 s51, s16, 31
	s_mul_hi_i32 s16, s16, 0x2800
	s_mul_i32 s17, s50, 0x2800
	v_cmp_lt_u32_e64 s[8:9], v6, v2
	v_cmp_gt_u32_e64 s[10:11], v6, v2
	v_lshlrev_b32_e32 v13, 1, v7
	v_lshl_or_b32 v6, v186, 4, s17
	v_mov_b32_e32 v7, s16
	v_readlane_b32 s16, v254, 7
	v_readlane_b32 s17, v254, 8
	v_or_b32_e32 v3, 3, v3
	s_mov_b32 s40, s16
	s_ashr_i32 s41, s16, 31
	s_mul_hi_i32 s35, s16, 0x2800
	s_mul_i32 s34, s16, 0x2800
	s_lshl_b64 s[16:17], s[50:51], 8
	v_lshl_or_b32 v5, v2, 7, v1
	v_lshlrev_b32_e32 v11, 2, v2
	v_cmp_lt_u32_e32 vcc, v8, v2
	v_cmp_lt_u32_e64 s[12:13], v3, v2
	v_cmp_gt_u32_e64 s[14:15], v3, v2
	v_lshl_or_b32 v2, v186, 2, s16
	v_mov_b32_e32 v3, s17
	s_mov_b64 s[16:17], 0x91100000
	v_readlane_b32 s2, v254, 9
	v_lshl_add_u64 v[8:9], v[2:3], 0, s[16:17]
	s_mov_b32 s16, s40
	v_readlane_b32 s3, v254, 10
	s_lshl_b32 s2, s2, 14
	v_writelane_b32 v254, s16, 7
	s_add_i32 s53, s2, 0
	v_lshlrev_b32_e32 v4, 5, v186
	v_writelane_b32 v254, s17, 8
	s_mov_b32 s43, 1.0
	s_mov_b32 s42, s50
	s_mov_b32 s52, 0
	v_cmp_eq_u32_e64 s[2:3], 0, v186
	v_lshl_add_u32 v1, v186, 1, s53
	s_lshl_b64 s[36:37], s[40:41], 8
	s_lshl_b64 s[38:39], s[50:51], 4
	s_lshl_b64 s[40:41], s[40:41], 4
	v_mov_b32_e32 v3, 0
	v_mov_b32_e32 v52, 0xc00
	s_mov_b64 s[48:49], 0xc00
	v_add_u32_e32 v53, s53, v4
	v_add_u32_e32 v54, s53, v5
	v_add_u32_e32 v55, s53, v10
	v_add_u32_e32 v56, s53, v11
	v_add_u32_e32 v57, s53, v13
	v_add_u32_e32 v58, s53, v12
	v_mov_b32_e32 v11, 1.0
	s_or_b64 s[16:17], s[8:9], vcc
	v_writelane_b32 v254, s42, 11
	s_mov_b32 s54, s50
	s_nop 0
	v_writelane_b32 v254, s43, 12
	s_branch .LBB0_856

; DI void chunk_prep(const bf16* PROJ, const float* mu, const bf16* LO, const float* pw0, const float* pa0, const float* pkk, const float* pka, const float* prk, float* SCAL, unsigned char* OPS, float* G15, LAS unsigned char* lds, int gw, int NGW, int wave, int lane) {
;     ...
;             for (int t = 0; t < 16; ++t) {
;                 const float z = -(w0v + wl[t]);
;                 w[t] = __builtin_amdgcn_exp2f(-1.4426950408889634f * 0.6065306597126334f * __builtin_amdgcn_rcpf(1.f + __builtin_amdgcn_exp2f(1.4426950408889634f * z)));
;                 av[t] = __builtin_amdgcn_rcpf(1.f + __builtin_amdgcn_exp2f(-1.4426950408889634f * (a0v + al[t])));
;                 const float kx = k[t] * kkv; a[t] = kx; nn[t] = kx * kx;
;                 const float kp = k[t] * (1.f + (av[t] - 1.f) * kav); k[t] = kp; bo[t] = r[t] * kp * rkv;
;             }
; #pragma unroll
;             for (int t = 0; t < 16; ++t) { { auto rr = __builtin_amdgcn_permlane32_swap(__float_as_uint(nn[t]), __float_as_uint(nn[t]), false, false); nn[t] = __uint_as_float(rr[0]) + __uint_as_float(rr[1]); }
;                                            { auto rr = __builtin_amdgcn_permlane32_swap(__float_as_uint(bo[t]), __float_as_uint(bo[t]), false, false); bo[t] = __uint_as_float(rr[0]) + __uint_as_float(rr[1]); } }
;     ...
;             CP_DPP_STEP(0x128) CP_DPP_STEP(0x124) CP_DPP_STEP(0x122) CP_DPP_STEP(0x121)
;     ...
; #pragma unroll
;             for (int t = 0; t < 16; ++t) {
;                 const float nsum = __builtin_bit_cast(float, __builtin_amdgcn_readlane(__builtin_bit_cast(int, nn[t]), 0)) + __builtin_bit_cast(float, __builtin_amdgcn_readlane(__builtin_bit_cast(int, nn[t]), 16));
;                 const float bon = __builtin_bit_cast(float, __builtin_amdgcn_readlane(__builtin_bit_cast(int, bo[t]), 0)) + __builtin_bit_cast(float, __builtin_amdgcn_readlane(__builtin_bit_cast(int, bo[t]), 16));
;                 if (lane == 0) ((GAS float*)SCAL)[((m0 + t) * 8 + hd) * 4 + 2] = bon;
;                 const float kn = a[t] * __builtin_amdgcn_rsqf(fmaxf(nsum, 1e-24f));
;                 a[t] = -kn; b[t] = kn * av[t];
;             }
; #pragma unroll
;             for (int t = 0; t < 16; ++t) { const float gm1 = g; g *= w[t]; const float inv = __builtin_amdgcn_rcpf(g); a[t] *= gm1; r[t] *= g; b[t] *= inv; k[t] *= inv; }
;         }
;         ((GAS float*)G15)[(size_t)task * 64 + d] = g;
; #pragma unroll
.Lmy_cps_skip_loop:
	v_lshlrev_b32_e32 v77, 16, v77
	v_exp_f32_e32 v84, v74
	v_mul_f32_e32 v74, 0xbf60028a, v79
	v_mul_f32_e32 v10, v10, v97
	v_mul_f32_e32 v81, 0xbfb8aa3b, v81
	v_lshlrev_b32_e32 v78, 16, v78
	v_add_f32_e32 v73, v59, v73
	v_exp_f32_e32 v97, v74
	v_add_f32_e32 v74, 1.0, v76
	v_add_f32_e32 v76, v59, v77
	v_exp_f32_e32 v81, v81
	v_mul_f32_e32 v73, 0xbfb8aa3b, v73
	v_mul_f32_e32 v76, 0xbfb8aa3b, v76
	v_add_f32_e32 v77, v59, v78
	v_lshlrev_b32_e32 v48, 16, v48
	v_exp_f32_e32 v73, v73
	v_exp_f32_e32 v76, v76
	v_mul_f32_e32 v77, 0xbfb8aa3b, v77
	v_exp_f32_e32 v77, v77
	v_add_f32_e32 v48, v59, v48
	v_mul_f32_e32 v48, 0xbfb8aa3b, v48
	v_add_f32_e32 v81, 1.0, v81
	v_exp_f32_e32 v48, v48
	v_rcp_f32_e32 v81, v81
	v_lshlrev_b32_e32 v75, 16, v75
	v_add_f32_e32 v73, 1.0, v73
	v_rcp_f32_e32 v74, v74
	v_add_f32_e32 v76, 1.0, v76
	v_rcp_f32_e32 v73, v73
	v_rcp_f32_e32 v76, v76
	v_add_f32_e32 v77, 1.0, v77
	v_add_f32_e32 v75, v59, v75
	v_rcp_f32_e32 v77, v77
	v_mul_f32_e32 v75, 0xbfb8aa3b, v75
	v_exp_f32_e32 v75, v75
	v_add_f32_e32 v48, 1.0, v48
	v_lshlrev_b32_e32 v43, 16, v43
	v_mul_f32_e32 v81, 0xbf60028a, v81
	v_mul_f32_e32 v74, 0xbf60028a, v74
	v_rcp_f32_e32 v48, v48
	v_exp_f32_e32 v81, v81
	v_mul_f32_e32 v73, 0xbf60028a, v73
	v_exp_f32_e32 v99, v74
	v_mul_f32_e32 v74, 0xbf60028a, v76
	v_add_f32_e32 v43, v59, v43
	v_exp_f32_e32 v73, v73
	v_exp_f32_e32 v100, v74
	v_mul_f32_e32 v74, 0xbf60028a, v77
	v_mul_f32_e32 v43, 0xbfb8aa3b, v43
	v_exp_f32_e32 v43, v43
	v_exp_f32_e32 v101, v74
	v_add_f32_e32 v74, 1.0, v75
	v_rcp_f32_e32 v74, v74
	v_mul_f32_e32 v48, 0xbf60028a, v48
	v_exp_f32_e32 v102, v48
	v_mul_f32_e32 v48, v81, v96
	v_mul_f32_e32 v41, v41, v49
	v_mul_f32_e64 v96, v81, -v49
	v_mul_f32_e32 v49, v48, v73
	v_add_f32_e32 v43, 1.0, v43
	v_rcp_f32_e32 v75, v48
	v_mul_f32_e32 v63, v63, v48
	v_mul_f32_e64 v73, v48, -v89
	v_mul_f32_e32 v48, v49, v83
	v_mul_f32_e32 v29, v29, v91
	v_mul_f32_e32 v28, v28, v89
	v_rcp_f32_e32 v43, v43
	v_mul_f32_e32 v59, 0xbf60028a, v74
	v_max_f32_e32 v74, 0x179abe15, v98
	v_rcp_f32_e32 v76, v49
	v_mul_f32_e32 v89, v61, v49
	v_mul_f32_e64 v91, v49, -v91
	v_mul_f32_e32 v49, v48, v82
	v_rsq_f32_e32 v74, v74
	v_mul_f32_e32 v103, v62, v81
	v_rcp_f32_e32 v77, v48
	v_mul_f32_e32 v104, v60, v48
	v_mul_f32_e64 v62, v48, -v92
	v_mul_f32_e32 v48, v49, v80
	v_rcp_f32_e32 v78, v49
	v_mul_f32_e32 v64, v64, v49
	v_mul_f32_e64 v61, v49, -v93
	v_mul_f32_e32 v49, v48, v85
	v_mul_f32_e32 v38, v38, v92
	v_mul_f32_e32 v92, v2, v49
	v_mul_f32_e32 v2, v49, v86
	v_mul_f32_e32 v43, 0xbf60028a, v43
	v_rcp_f32_e32 v79, v48
	v_mul_f32_e32 v65, v65, v48
	v_mul_f32_e64 v60, v48, -v94
	v_mul_f32_e32 v48, v2, v84
	v_exp_f32_e32 v43, v43
	v_exp_f32_e32 v98, v59
	v_mul_f32_e32 v42, v42, v74
	v_rcp_f32_e32 v74, v81
	v_rcp_f32_e32 v80, v49
	v_rcp_f32_e32 v81, v2
	v_mul_f32_e64 v59, v49, -v95
	v_mul_f32_e32 v67, v67, v2
	v_mul_f32_e64 v49, v2, -v44
	v_mul_f32_e32 v2, v48, v97
	v_mul_f32_e32 v36, v36, v44
	v_mul_f32_e32 v44, v2, v99
	v_mul_f32_e32 v34, v34, v47
	v_rcp_f32_e32 v83, v2
	v_mul_f32_e32 v86, v71, v2
	v_mul_f32_e64 v47, v2, -v47
	v_mul_f32_e32 v2, v44, v100
	v_mul_f32_e32 v35, v35, v46
	v_mul_f32_e32 v39, v39, v93
	v_rcp_f32_e32 v84, v44
	v_mul_f32_e32 v93, v70, v44
	v_mul_f32_e64 v46, v44, -v46
	v_mul_f32_e32 v44, v2, v101
	v_mul_f32_e32 v37, v37, v45
	v_mul_f32_e32 v30, v30, v94
	v_rcp_f32_e32 v82, v48
	v_mul_f32_e32 v66, v66, v48
	v_mul_f32_e64 v48, v48, -v45
	v_rcp_f32_e32 v85, v2
	v_mul_f32_e32 v94, v69, v2
	v_mul_f32_e64 v45, v2, -v90
	v_mul_f32_e32 v2, v44, v43
	v_mul_f32_e32 v31, v31, v95
	v_mul_f32_e32 v95, v2, v98
	v_mul_f32_e32 v33, v33, v88
	v_mul_f32_e32 v32, v32, v90
	v_rcp_f32_e32 v70, v44
	v_mul_f32_e32 v90, v68, v44
	v_mul_f32_e64 v44, v44, -v88
	v_mul_f32_e32 v88, v72, v2
	v_mul_f32_e32 v72, v95, v102
	v_mul_f32_e32 v26, v26, v87
	v_mul_f32_e32 v27, v27, v42
	v_rcp_f32_e32 v68, v95
	v_mul_f32_e64 v43, v2, -v87
	v_mul_f32_e32 v87, v51, v95
	v_mul_f32_e64 v42, v95, -v42
	v_mul_f32_e32 v95, v50, v72
	v_lshl_add_u64 v[50:51], s[44:45], 0, v[8:9]
	global_store_dword v[50:51], v72, off
	v_cvt_pk_bf16_f32 v50, v103, s0
	ds_write_b16 v1, v50 offset:2048
	v_cvt_pk_bf16_f32 v50, v96, s0
	ds_write_b16 v1, v50 offset:128
	v_cvt_pk_bf16_f32 v50, v63, s0
	ds_write_b16 v1, v50 offset:2176
	v_cvt_pk_bf16_f32 v50, v73, s0
	ds_write_b16 v1, v50 offset:256
	v_cvt_pk_bf16_f32 v50, v89, s0
	ds_write_b16 v1, v50 offset:2304
	v_cvt_pk_bf16_f32 v50, v91, s0
	ds_write_b16 v1, v50 offset:384
	v_cvt_pk_bf16_f32 v50, v104, s0
	ds_write_b16 v1, v50 offset:2432
	v_cvt_pk_bf16_f32 v50, v62, s0
	ds_write_b16 v1, v50 offset:512
	v_cvt_pk_bf16_f32 v50, v64, s0
	ds_write_b16 v1, v50 offset:2560
	v_cvt_pk_bf16_f32 v50, v61, s0
	ds_write_b16 v1, v50 offset:640
	v_cvt_pk_bf16_f32 v50, v65, s0
	ds_write_b16 v1, v50 offset:2688
	v_cvt_pk_bf16_f32 v50, v60, s0
	ds_write_b16 v1, v50 offset:768
	v_cvt_pk_bf16_f32 v50, v92, s0
	ds_write_b16 v1, v50 offset:2816
	v_cvt_pk_bf16_f32 v50, v59, s0
	ds_write_b16 v1, v50 offset:896
	v_cvt_pk_bf16_f32 v50, v67, s0
	ds_write_b16 v1, v50 offset:2944
	v_cvt_pk_bf16_f32 v50, v49, s0
	ds_write_b16 v1, v50 offset:1024
	v_cvt_pk_bf16_f32 v50, v66, s0
	ds_write_b16 v1, v50 offset:3072
	v_cvt_pk_bf16_f32 v50, v48, s0
	ds_write_b16 v1, v50 offset:1152
	v_cvt_pk_bf16_f32 v50, v86, s0
	ds_write_b16 v1, v50 offset:3200
	v_cvt_pk_bf16_f32 v50, v47, s0
	ds_write_b16 v1, v50 offset:1280
	v_cvt_pk_bf16_f32 v50, v93, s0
	ds_write_b16 v1, v50 offset:3328
	v_cvt_pk_bf16_f32 v50, v46, s0
	ds_write_b16 v1, v50 offset:1408
	v_cvt_pk_bf16_f32 v50, v94, s0
	ds_write_b16 v1, v50 offset:3456
	v_cvt_pk_bf16_f32 v50, v45, s0
	ds_write_b16 v1, v50 offset:1536
; #define LAS __attribute__((address_space(3)))
; DI unsigned cvtpk(float lo, float hi) { typedef float f2 __attribute__((ext_vector_type(2))); typedef __bf16 b2 __attribute__((ext_vector_type(2))); f2 v = {lo, hi}; b2 b = __builtin_convertvector(v, b2); return __builtin_bit_cast(unsigned, b); }
; DI unsigned short cvt1(float x) { return (unsigned short)(cvtpk(x, 0.f) & 0xffffu); }
; DI void chunk_prep(const bf16* PROJ, const float* mu, const bf16* LO, const float* pw0, const float* pa0, const float* pkk, const float* pka, const float* prk, float* SCAL, unsigned char* OPS, float* G15, LAS unsigned char* lds, int gw, int NGW, int wave, int lane) {
;     ...
; #pragma unroll
;         for (int t = 0; t < 16; ++t) {
;             *(LAS unsigned short*)(base + L_AT + (t * 64 + d) * 2) = cvt1(a[t]); *(LAS unsigned short*)(base + L_RT + (t * 64 + d) * 2) = cvt1(r[t]);
;             *(LAS unsigned short*)(base + L_BT + (t * 64 + d) * 2) = cvt1(b[t]); *(LAS unsigned short*)(base + L_KT + (t * 64 + d) * 2) = cvt1(k[t]); }
;         { v4u h0, h1, k0, k1;
;           h0.x = cvtpk(b[0] * g, b[1] * g); h0.y = cvtpk(b[2] * g, b[3] * g); h0.z = cvtpk(b[4] * g, b[5] * g); h0.w = cvtpk(b[6] * g, b[7] * g);
;           h1.x = cvtpk(b[8] * g, b[9] * g); h1.y = cvtpk(b[10] * g, b[11] * g); h1.z = cvtpk(b[12] * g, b[13] * g); h1.w = cvtpk(b[14] * g, b[15] * g);
;           k0.x = cvtpk(k[0] * g, k[1] * g); k0.y = cvtpk(k[2] * g, k[3] * g); k0.z = cvtpk(k[4] * g, k[5] * g); k0.w = cvtpk(k[6] * g, k[7] * g);
;           k1.x = cvtpk(k[8] * g, k[9] * g); k1.y = cvtpk(k[10] * g, k[11] * g); k1.z = cvtpk(k[12] * g, k[13] * g); k1.w = cvtpk(k[14] * g, k[15] * g);
;           *(LAS v4u*)(base + L_BH + d * 32) = h0; *(LAS v4u*)(base + L_BH + d * 32 + 16) = h1; *(LAS v4u*)(base + L_KH + d * 32) = k0; *(LAS v4u*)(base + L_KH + d * 32 + 16) = k1; }
;         CS_LWAIT();
;         { f4 gab = {0.f, 0.f, 0.f, 0.f}, gak = gab, grb = gab, grk = gab;
; #pragma unroll
;           for (int kb = 0; kb < 2; ++kb) { const int fo = (x * 64 + 32 * kb + 8 * q) * 2;
;               const bf16x8 fa = *(const LAS bf16x8*)(base + L_AT + fo), fr = *(const LAS bf16x8*)(base + L_RT + fo), fb = *(const LAS bf16x8*)(base + L_BT + fo), fk = *(const LAS bf16x8*)(base + L_KT + fo);
;               gab = CS_MFMA(fb, fa, gab); gak = CS_MFMA(fk, fa, gak); grb = CS_MFMA(fb, fr, grb); grk = CS_MFMA(fk, fr, grk); }
	v_cvt_pk_bf16_f32 v50, v90, s0
	ds_write_b16 v1, v50 offset:3584
	v_cvt_pk_bf16_f32 v50, v44, s0
	ds_write_b16 v1, v50 offset:1664
	v_cvt_pk_bf16_f32 v50, v88, s0
	ds_write_b16 v1, v50 offset:3712
	v_cvt_pk_bf16_f32 v50, v43, s0
	ds_write_b16 v1, v50 offset:1792
	v_cvt_pk_bf16_f32 v50, v87, s0
	v_mul_f32_e32 v40, v40, v10
	ds_write_b16 v1, v50 offset:3840
	v_cvt_pk_bf16_f32 v50, v42, s0
	ds_write_b16 v1, v50 offset:1920
	v_cvt_pk_bf16_f32 v50, v95, s0
	v_pk_mul_f32 v[40:41], v[74:75], v[40:41]
	ds_write_b16 v1, v50 offset:3968
	v_cvt_pk_bf16_f32 v50, v40, s0
	ds_write_b16 v1, v50 offset:4096
	v_cvt_pk_bf16_f32 v50, v41, s0
	v_pk_mul_f32 v[40:41], v[72:73], v[40:41] op_sel_hi:[0,1]
	v_pk_mul_f32 v[28:29], v[76:77], v[28:29]
	v_cvt_pk_bf16_f32 v64, v40, v41
	v_cvt_pk_bf16_f32 v40, v28, s0
	ds_write_b16 v1, v40 offset:4352
	v_cvt_pk_bf16_f32 v40, v29, s0
	v_pk_mul_f32 v[28:29], v[72:73], v[28:29] op_sel_hi:[0,1]
	v_cvt_pk_bf16_f32 v65, v28, v29
	v_pk_mul_f32 v[28:29], v[78:79], v[38:39]
	v_rcp_f32_e32 v71, v2
	v_cvt_pk_bf16_f32 v38, v28, s0
	ds_write_b16 v1, v38 offset:4608
	v_cvt_pk_bf16_f32 v38, v29, s0
	v_pk_mul_f32 v[28:29], v[72:73], v[28:29] op_sel_hi:[0,1]
	v_cvt_pk_bf16_f32 v66, v28, v29
	v_pk_mul_f32 v[28:29], v[80:81], v[30:31]
	v_rcp_f32_e32 v69, v72
	v_cvt_pk_bf16_f32 v30, v28, s0
	ds_write_b16 v1, v30 offset:4864
	v_cvt_pk_bf16_f32 v30, v29, s0
	v_pk_mul_f32 v[28:29], v[72:73], v[28:29] op_sel_hi:[0,1]
	v_cvt_pk_bf16_f32 v67, v28, v29
	v_pk_mul_f32 v[28:29], v[82:83], v[36:37]
	ds_write_b16 v1, v30 offset:4992
	v_cvt_pk_bf16_f32 v30, v28, s0
	ds_write_b16 v1, v30 offset:5120
	v_cvt_pk_bf16_f32 v30, v29, s0
	ds_write_b16 v1, v30 offset:5248
	v_pk_mul_f32 v[28:29], v[72:73], v[28:29] op_sel_hi:[0,1]
	v_pk_mul_f32 v[30:31], v[84:85], v[34:35]
	v_cvt_pk_bf16_f32 v28, v28, v29
	v_cvt_pk_bf16_f32 v29, v30, s0
	ds_write_b16 v1, v29 offset:5376
	v_cvt_pk_bf16_f32 v29, v31, s0
	v_pk_mul_f32 v[30:31], v[72:73], v[30:31] op_sel_hi:[0,1]
	ds_write_b16 v1, v29 offset:5504
	v_cvt_pk_bf16_f32 v29, v30, v31
	v_pk_mul_f32 v[30:31], v[70:71], v[32:33]
	v_pk_mul_f32 v[26:27], v[68:69], v[26:27]
	v_cvt_pk_bf16_f32 v32, v30, s0
	ds_write_b16 v1, v32 offset:5632
	v_cvt_pk_bf16_f32 v32, v31, s0
	v_pk_mul_f32 v[30:31], v[72:73], v[30:31] op_sel_hi:[0,1]
	v_cvt_pk_bf16_f32 v30, v30, v31
	v_cvt_pk_bf16_f32 v31, v26, s0
	ds_write_b16 v1, v31 offset:5888
	v_cvt_pk_bf16_f32 v31, v27, s0
	v_pk_mul_f32 v[26:27], v[72:73], v[26:27] op_sel_hi:[0,1]
	v_pk_mul_f32 v[4:5], v[74:75], v[4:5]
	ds_write_b16 v1, v31 offset:6016
	v_cvt_pk_bf16_f32 v31, v26, v27
	v_cvt_pk_bf16_f32 v26, v4, s0
	ds_write_b16 v1, v26 offset:6144
	v_cvt_pk_bf16_f32 v26, v5, s0
	v_pk_mul_f32 v[4:5], v[4:5], v[72:73] op_sel_hi:[1,0]
	ds_write_b16 v1, v32 offset:5760
	v_cvt_pk_bf16_f32 v32, v4, v5
	v_pk_mul_f32 v[4:5], v[76:77], v[12:13]
	v_cvt_pk_bf16_f32 v2, -v10, s0
	v_cvt_pk_bf16_f32 v12, v4, s0
	ds_write_b16 v1, v12 offset:6400
	v_cvt_pk_bf16_f32 v12, v5, s0
	v_pk_mul_f32 v[4:5], v[4:5], v[72:73] op_sel_hi:[1,0]
	ds_write_b16 v1, v12 offset:6528
	v_cvt_pk_bf16_f32 v33, v4, v5
	v_pk_mul_f32 v[4:5], v[78:79], v[14:15]
	ds_write_b16 v1, v2
	v_cvt_pk_bf16_f32 v12, v4, s0
	ds_write_b16 v1, v12 offset:6656
	v_cvt_pk_bf16_f32 v12, v5, s0
	v_pk_mul_f32 v[4:5], v[4:5], v[72:73] op_sel_hi:[1,0]
	ds_write_b16 v1, v12 offset:6784
	v_cvt_pk_bf16_f32 v34, v4, v5
	v_pk_mul_f32 v[4:5], v[80:81], v[16:17]
	ds_write_b16 v1, v50 offset:4224
	v_cvt_pk_bf16_f32 v12, v4, s0
	ds_write_b16 v1, v12 offset:6912
	v_cvt_pk_bf16_f32 v12, v5, s0
	v_pk_mul_f32 v[4:5], v[4:5], v[72:73] op_sel_hi:[1,0]
	ds_write_b16 v1, v12 offset:7040
	v_cvt_pk_bf16_f32 v35, v4, v5
	v_pk_mul_f32 v[4:5], v[82:83], v[18:19]
	ds_write_b16 v1, v40 offset:4480
	v_cvt_pk_bf16_f32 v12, v4, s0
	ds_write_b16 v1, v12 offset:7168
	v_cvt_pk_bf16_f32 v12, v5, s0
	v_pk_mul_f32 v[4:5], v[4:5], v[72:73] op_sel_hi:[1,0]
	ds_write_b16 v1, v12 offset:7296
	v_cvt_pk_bf16_f32 v12, v4, v5
	v_pk_mul_f32 v[4:5], v[84:85], v[20:21]
	ds_write_b16 v1, v38 offset:4736
	v_cvt_pk_bf16_f32 v13, v4, s0
	ds_write_b16 v1, v13 offset:7424
	v_cvt_pk_bf16_f32 v13, v5, s0
	v_pk_mul_f32 v[4:5], v[4:5], v[72:73] op_sel_hi:[1,0]
	ds_write_b16 v1, v13 offset:7552
	v_cvt_pk_bf16_f32 v13, v4, v5
	v_pk_mul_f32 v[4:5], v[70:71], v[22:23]
	ds_write_b16 v1, v26 offset:6272
	v_cvt_pk_bf16_f32 v14, v4, s0
	ds_write_b16 v1, v14 offset:7680
	v_cvt_pk_bf16_f32 v14, v5, s0
	v_pk_mul_f32 v[4:5], v[4:5], v[72:73] op_sel_hi:[1,0]
	ds_write_b16 v1, v14 offset:7808
	v_cvt_pk_bf16_f32 v14, v4, v5
	v_pk_mul_f32 v[4:5], v[68:69], v[24:25]
	s_or_b64 vcc, s[16:17], s[4:5]
	v_cvt_pk_bf16_f32 v15, v4, s0
	ds_write_b16 v1, v15 offset:7936
	v_cvt_pk_bf16_f32 v15, v5, s0
	v_pk_mul_f32 v[4:5], v[72:73], v[4:5] op_sel_hi:[0,1]
	ds_write_b16 v1, v15 offset:8064
	v_cvt_pk_bf16_f32 v15, v4, v5
	ds_write_b128 v53, v[64:67] offset:8192
	ds_write_b128 v53, v[28:31] offset:8208
	ds_write_b128 v53, v[32:35] offset:10240
	ds_write_b128 v53, v[12:15] offset:10256
	s_waitcnt lgkmcnt(0)
	ds_read_b128 v[12:15], v54 offset:4096
	ds_read_b128 v[16:19], v54
	ds_read_b128 v[20:23], v54 offset:64
	ds_read_b128 v[24:27], v54 offset:4160
	ds_read_b128 v[32:35], v54 offset:6144
	ds_read_b128 v[36:39], v54 offset:6208
	ds_read_b128 v[64:67], v54 offset:2048
	ds_read_b128 v[68:71], v54 offset:2112
	s_waitcnt lgkmcnt(6)
	v_mfma_f32_16x16x32_bf16 v[28:31], v[12:15], v[16:19], 0
	v_mov_b32_e32 v4, s52
	s_mov_b32 s42, 0x87100000
	v_readlane_b32 s50, v254, 7
	s_waitcnt lgkmcnt(1)
; #define LAS __attribute__((address_space(3)))
; #define CS_MFMA(a, b, c) __builtin_amdgcn_mfma_f32_16x16x32_bf16((a), (b), (c), 0, 0, 0)
; #define CS_LWAIT() asm volatile("s_waitcnt lgkmcnt(0)" ::: "memory")
; DI void chunk_prep(const bf16* PROJ, const float* mu, const bf16* LO, const float* pw0, const float* pa0, const float* pkk, const float* pka, const float* prk, float* SCAL, unsigned char* OPS, float* G15, LAS unsigned char* lds, int gw, int NGW, int wave, int lane) {
;     ...
;           for (int kb = 0; kb < 2; ++kb) { const int fo = (x * 64 + 32 * kb + 8 * q) * 2;
;               const bf16x8 fa = *(const LAS bf16x8*)(base + L_AT + fo), fr = *(const LAS bf16x8*)(base + L_RT + fo), fb = *(const LAS bf16x8*)(base + L_BT + fo), fk = *(const LAS bf16x8*)(base + L_KT + fo);
;               gab = CS_MFMA(fb, fa, gab); gak = CS_MFMA(fk, fa, gak); grb = CS_MFMA(fb, fr, grb); grk = CS_MFMA(fk, fr, grk); }
; #pragma unroll
;           for (int rr = 0; rr < 4; ++rr) { const int u = 4 * q + rr; if (!(u < x)) { gab[rr] = 0.f; gak[rr] = 0.f; } if (!(u <= x)) { grb[rr] = 0.f; grk[rr] = 0.f; } }
;           const int go = (x * 16 + 4 * q) * 4;
;           *(LAS f4*)(base + L_AB + go) = gab; *(LAS f4*)(base + L_AK + go) = gak; *(LAS f4*)(base + L_RB + go) = grb; *(LAS f4*)(base + L_RK + go) = grk; }
;         CS_LWAIT();
;         float mm[16];
; #pragma unroll
;         for (int t = 0; t < 16; ++t) mm[t] = *(const LAS float*)(base + L_AK + (t * 16 + x) * 4);
; #pragma unroll
;         for (int t = 1; t < 16; ++t) {
;             float ab[16];
; #pragma unroll
;             for (int u4 = 0; u4 < 4; ++u4) if (4 * u4 < t) { const f4 v = *(const LAS f4*)(base + L_AB + (t * 16 + 4 * u4) * 4); ab[4 * u4] = v.x; ab[4 * u4 + 1] = v.y; ab[4 * u4 + 2] = v.z; ab[4 * u4 + 3] = v.w; }
; #pragma unroll
;             for (int u = 0; u < 16; ++u) if (u < t) { a[t] = fmaf(a[u], ab[u], a[t]); mm[t] = fmaf(mm[u], ab[u], mm[t]); }
	v_mfma_f32_16x16x32_bf16 v[12:15], v[12:15], v[64:67], 0
	s_add_i32 s54, s54, s50
	s_add_u32 s38, s38, s40
	s_addc_u32 s39, s39, s41
	v_mfma_f32_16x16x32_bf16 v[16:19], v[32:35], v[16:19], 0
	s_cmpk_lt_i32 s54, 0x4000
	v_lshl_add_u64 v[8:9], v[8:9], 0, s[36:37]
	v_readlane_b32 s51, v254, 8
	v_mfma_f32_16x16x32_bf16 v[32:35], v[32:35], v[64:67], 0
	s_waitcnt lgkmcnt(0)
	v_mfma_f32_16x16x32_bf16 v[12:15], v[24:27], v[68:71], v[12:15]
	v_mfma_f32_16x16x32_bf16 v[28:31], v[24:27], v[20:23], v[28:31]
	v_mov_b32_e32 v26, s52
	v_mov_b32_e32 v24, s52
	s_nop 4
	v_cndmask_b32_e64 v25, v12, v26, s[6:7]
	v_mfma_f32_16x16x32_bf16 v[16:19], v[36:39], v[20:23], v[16:19]
	v_cndmask_b32_e64 v12, v25, v12, s[4:5]
	v_cndmask_b32_e64 v26, 0, v30, s[8:9]
	v_cndmask_b32_e64 v25, 0, v29, s[16:17]
	v_mfma_f32_16x16x32_bf16 v[20:23], v[36:39], v[68:71], v[32:35]
	v_cndmask_b32_e64 v27, 0, v31, s[12:13]
	s_nop 2
	v_cndmask_b32_e32 v16, v24, v16, vcc
	v_cndmask_b32_e32 v24, v4, v28, vcc
	v_mov_b32_e32 v32, s52
	v_cndmask_b32_e64 v13, 0, v13, s[4:5]
	v_cndmask_b32_e64 v5, v20, v32, s[6:7]
	v_cndmask_b32_e64 v20, v5, v20, s[4:5]
	v_cndmask_b32_e64 v21, 0, v21, s[4:5]
	v_cndmask_b32_e64 v18, 0, v18, s[8:9]
	v_cndmask_b32_e64 v17, 0, v17, s[16:17]
	v_cndmask_b32_e64 v22, v22, 0, s[10:11]
	v_cndmask_b32_e64 v14, v14, 0, s[10:11]
	v_cndmask_b32_e64 v19, 0, v19, s[12:13]
	v_cndmask_b32_e64 v23, v23, 0, s[14:15]
	v_cndmask_b32_e64 v15, v15, 0, s[14:15]
	ds_write_b128 v55, v[24:27] offset:12288
	ds_write_b128 v55, v[16:19] offset:13312
	ds_write_b128 v55, v[12:15] offset:14336
	ds_write_b128 v55, v[20:23] offset:15360
	s_waitcnt lgkmcnt(0)
	v_add_u32_e32 v26, 0x3400, v56
	v_mov_b32_e32 v29, s53
	ds_read2_b32 v[22:23], v26 offset1:16
	ds_read2_b32 v[18:19], v26 offset0:32 offset1:48
	ds_read2_b32 v[14:15], v26 offset0:64 offset1:80
	ds_read2_b32 v[12:13], v26 offset0:96 offset1:112
	ds_read2_b32 v[4:5], v26 offset0:128 offset1:144
	ds_read_b128 v[30:33], v29 offset:12352
	ds_read2_b32 v[16:17], v26 offset0:160 offset1:176
	s_waitcnt lgkmcnt(1)
	ds_read_b128 v[32:35], v29 offset:12416
	ds_read2_b32 v[24:25], v26 offset0:192 offset1:208
	ds_read2_b32 v[20:21], v26 offset0:224 offset1:240
	s_waitcnt lgkmcnt(2)
	ds_read_b128 v[34:37], v29 offset:12480
	ds_read_b128 v[38:41], v29 offset:12544
	v_fma_f32 v27, -v10, v30, v96
	v_fma_f32 v23, v22, v30, v23
	v_fma_f32 v28, -v10, v32, v73
	v_fma_f32 v18, v22, v32, v18
	s_waitcnt lgkmcnt(1)
	v_fma_f32 v30, -v10, v34, v91
	v_fmac_f32_e32 v19, v22, v34
	v_fmac_f32_e32 v28, v27, v33
	v_fmac_f32_e32 v18, v23, v33
	v_fmac_f32_e32 v30, v27, v35
	v_fmac_f32_e32 v19, v23, v35
	v_fmac_f32_e32 v30, v28, v36
	v_fmac_f32_e32 v19, v18, v36
	ds_read_b128 v[34:37], v29 offset:12608
	s_waitcnt lgkmcnt(1)
	v_fma_f32 v31, -v10, v38, v62
	v_fma_f32 v14, v22, v38, v14
	v_fmac_f32_e32 v31, v27, v39
	v_fmac_f32_e32 v14, v23, v39
	v_fmac_f32_e32 v31, v28, v40
	v_fmac_f32_e32 v14, v18, v40
	v_fmac_f32_e32 v31, v30, v41
	v_fmac_f32_e32 v14, v19, v41
	ds_read_b128 v[38:41], v29 offset:12624
	s_waitcnt lgkmcnt(1)
	v_fma_f32 v32, -v10, v34, v61
	v_fmac_f32_e32 v15, v22, v34
	ds_read_b128 v[62:65], v29 offset:12672
	v_fmac_f32_e32 v32, v27, v35
	v_fmac_f32_e32 v15, v23, v35
	v_fmac_f32_e32 v32, v28, v36
	v_fmac_f32_e32 v15, v18, v36
	v_fmac_f32_e32 v32, v30, v37
	v_fmac_f32_e32 v15, v19, v37
	ds_read_b128 v[34:37], v29 offset:12688
	s_waitcnt lgkmcnt(2)
	v_fmac_f32_e32 v32, v31, v38
	v_fmac_f32_e32 v15, v14, v38
	s_waitcnt lgkmcnt(0)
	ds_read_b128 v[36:39], v29 offset:12736
	v_fma_f32 v33, -v10, v62, v60
	v_fma_f32 v12, v22, v62, v12
	v_fmac_f32_e32 v33, v27, v63
	v_fmac_f32_e32 v12, v23, v63
	v_fmac_f32_e32 v33, v28, v64
	v_fmac_f32_e32 v12, v18, v64
	v_fmac_f32_e32 v33, v30, v65
	v_fmac_f32_e32 v12, v19, v65
	v_fmac_f32_e32 v33, v31, v34
	v_fmac_f32_e32 v12, v14, v34
	ds_read_b128 v[60:63], v29 offset:12752
	s_waitcnt lgkmcnt(1)
	v_fma_f32 v34, -v10, v36, v59
	v_fmac_f32_e32 v13, v22, v36
	v_fmac_f32_e32 v34, v27, v37
	v_fmac_f32_e32 v13, v23, v37
	v_fmac_f32_e32 v34, v28, v38
	v_fmac_f32_e32 v13, v18, v38
	v_fmac_f32_e32 v34, v30, v39
	v_fmac_f32_e32 v13, v19, v39
	ds_read_b128 v[36:39], v29 offset:12800
	s_waitcnt lgkmcnt(1)
	v_fmac_f32_e32 v34, v31, v60
	v_fmac_f32_e32 v13, v14, v60
	v_fmac_f32_e32 v33, v32, v35
	v_fmac_f32_e32 v12, v15, v35
	v_fmac_f32_e32 v34, v32, v61
	v_fmac_f32_e32 v13, v15, v61
	v_fmac_f32_e32 v34, v33, v62
	v_fmac_f32_e32 v13, v12, v62
	ds_read_b128 v[60:63], v29 offset:12816
	s_waitcnt lgkmcnt(1)
	v_fma_f32 v35, -v10, v36, v49
	v_fma_f32 v4, v22, v36, v4
	v_fmac_f32_e32 v35, v27, v37
	v_fmac_f32_e32 v4, v23, v37
	v_fmac_f32_e32 v35, v28, v38
	v_fmac_f32_e32 v4, v18, v38
	v_fmac_f32_e32 v35, v30, v39
	v_fmac_f32_e32 v4, v19, v39
	ds_read_b128 v[36:39], v29 offset:12864
	s_waitcnt lgkmcnt(1)
	v_fmac_f32_e32 v35, v31, v60
	v_fmac_f32_e32 v4, v14, v60
	v_fmac_f32_e32 v35, v32, v61
	v_fmac_f32_e32 v4, v15, v61
	v_fmac_f32_e32 v35, v33, v62
	v_fmac_f32_e32 v4, v12, v62
	s_waitcnt lgkmcnt(0)
	v_fma_f32 v40, -v10, v36, v48
	v_fmac_f32_e32 v5, v22, v36
	v_fmac_f32_e32 v35, v34, v63
	v_fmac_f32_e32 v4, v13, v63
	ds_read_b128 v[60:63], v29 offset:12880
	ds_read_b128 v[64:67], v29 offset:12896
	v_fmac_f32_e32 v40, v27, v37
	v_fmac_f32_e32 v5, v23, v37
	v_fmac_f32_e32 v40, v28, v38
	v_fmac_f32_e32 v5, v18, v38
	v_fmac_f32_e32 v40, v30, v39
	v_fmac_f32_e32 v5, v19, v39
	ds_read_b128 v[36:39], v29 offset:12928
	s_waitcnt lgkmcnt(2)
	v_fmac_f32_e32 v40, v31, v60
	v_fmac_f32_e32 v5, v14, v60
	v_fmac_f32_e32 v40, v32, v61
	v_fmac_f32_e32 v5, v15, v61
	v_fmac_f32_e32 v40, v33, v62
	v_fmac_f32_e32 v5, v12, v62
	v_fmac_f32_e32 v40, v34, v63
	v_fmac_f32_e32 v5, v13, v63
	ds_read_b128 v[48:51], v29 offset:12944
	ds_read_b128 v[60:63], v29 offset:12960
	s_waitcnt lgkmcnt(2)
; #define LAS __attribute__((address_space(3)))
; DI void chunk_prep(const bf16* PROJ, const float* mu, const bf16* LO, const float* pw0, const float* pa0, const float* pkk, const float* pka, const float* prk, float* SCAL, unsigned char* OPS, float* G15, LAS unsigned char* lds, int gw, int NGW, int wave, int lane) {
;     ...
; #pragma unroll
;         for (int t = 1; t < 16; ++t) {
;             float ab[16];
; #pragma unroll
;             for (int u4 = 0; u4 < 4; ++u4) if (4 * u4 < t) { const f4 v = *(const LAS f4*)(base + L_AB + (t * 16 + 4 * u4) * 4); ab[4 * u4] = v.x; ab[4 * u4 + 1] = v.y; ab[4 * u4 + 2] = v.z; ab[4 * u4 + 3] = v.w; }
; #pragma unroll
;             for (int u = 0; u < 16; ++u) if (u < t) { a[t] = fmaf(a[u], ab[u], a[t]); mm[t] = fmaf(mm[u], ab[u], mm[t]); }
;         }
	v_fma_f32 v41, -v10, v36, v47
	v_fma_f32 v16, v22, v36, v16
	v_fmac_f32_e32 v41, v27, v37
	v_fmac_f32_e32 v16, v23, v37
	v_fmac_f32_e32 v41, v28, v38
	v_fmac_f32_e32 v16, v18, v38
	v_fmac_f32_e32 v41, v30, v39
	v_fmac_f32_e32 v16, v19, v39
	s_waitcnt lgkmcnt(1)
	v_fmac_f32_e32 v41, v31, v48
	v_fmac_f32_e32 v16, v14, v48
	ds_read_b128 v[36:39], v29 offset:12992
	v_fmac_f32_e32 v41, v32, v49
	v_fmac_f32_e32 v16, v15, v49
	v_fmac_f32_e32 v41, v33, v50
	v_fmac_f32_e32 v16, v12, v50
	v_fmac_f32_e32 v41, v34, v51
	v_fmac_f32_e32 v16, v13, v51
	v_fmac_f32_e32 v40, v35, v64
	v_fmac_f32_e32 v5, v4, v64
	s_waitcnt lgkmcnt(1)
	v_fmac_f32_e32 v41, v35, v60
	v_fmac_f32_e32 v16, v4, v60
	v_fmac_f32_e32 v41, v40, v61
	v_fmac_f32_e32 v16, v5, v61
	ds_read_b128 v[48:51], v29 offset:13008
	ds_read_b128 v[60:63], v29 offset:13024
	s_waitcnt lgkmcnt(2)
	v_fma_f32 v59, -v10, v36, v46
	v_fmac_f32_e32 v17, v22, v36
	v_fmac_f32_e32 v59, v27, v37
	v_fmac_f32_e32 v17, v23, v37
	v_fmac_f32_e32 v59, v28, v38
	v_fmac_f32_e32 v17, v18, v38
	v_fmac_f32_e32 v59, v30, v39
	v_fmac_f32_e32 v17, v19, v39
	s_waitcnt lgkmcnt(1)
	v_fmac_f32_e32 v59, v31, v48
	v_fmac_f32_e32 v17, v14, v48
	v_fmac_f32_e32 v59, v32, v49
	v_fmac_f32_e32 v17, v15, v49
	ds_read_b128 v[36:39], v29 offset:13056
	v_fmac_f32_e32 v59, v33, v50
	v_fmac_f32_e32 v17, v12, v50
	v_fmac_f32_e32 v59, v34, v51
	v_fmac_f32_e32 v17, v13, v51
	s_waitcnt lgkmcnt(1)
	v_fmac_f32_e32 v59, v35, v60
	v_fmac_f32_e32 v17, v4, v60
	v_fmac_f32_e32 v59, v40, v61
	v_fmac_f32_e32 v17, v5, v61
	v_fmac_f32_e32 v59, v41, v62
	v_fmac_f32_e32 v17, v16, v62
	ds_read_b128 v[46:49], v29 offset:13072
	ds_read_b128 v[60:63], v29 offset:13088
	s_waitcnt lgkmcnt(2)
	v_fma_f32 v68, -v10, v36, v45
	v_fma_f32 v24, v22, v36, v24
	v_fmac_f32_e32 v68, v27, v37
	v_fmac_f32_e32 v24, v23, v37
	v_fmac_f32_e32 v68, v28, v38
	v_fmac_f32_e32 v24, v18, v38
	v_fmac_f32_e32 v68, v30, v39
	v_fmac_f32_e32 v24, v19, v39
	s_waitcnt lgkmcnt(1)
	v_fmac_f32_e32 v68, v31, v46
	v_fmac_f32_e32 v24, v14, v46
	v_fmac_f32_e32 v68, v32, v47
	v_fmac_f32_e32 v24, v15, v47
	v_fmac_f32_e32 v68, v33, v48
	v_fmac_f32_e32 v24, v12, v48
	v_fmac_f32_e32 v68, v34, v49
	v_fmac_f32_e32 v24, v13, v49
	ds_read_b128 v[36:39], v29 offset:13120
	s_waitcnt lgkmcnt(1)
	v_fmac_f32_e32 v68, v35, v60
	v_fmac_f32_e32 v24, v4, v60
	v_fmac_f32_e32 v68, v40, v61
	v_fmac_f32_e32 v24, v5, v61
	v_fmac_f32_e32 v68, v41, v62
	v_fmac_f32_e32 v24, v16, v62
	v_fmac_f32_e32 v68, v59, v63
	v_fmac_f32_e32 v24, v17, v63
	ds_read_b128 v[46:49], v29 offset:13136
	ds_read_b128 v[60:63], v29 offset:13152
	ds_read_b128 v[64:67], v29 offset:13168
	s_waitcnt lgkmcnt(0)
	v_fma_f32 v65, -v10, v36, v44
	v_fmac_f32_e32 v25, v22, v36
	v_fmac_f32_e32 v65, v27, v37
	v_fmac_f32_e32 v25, v23, v37
	v_fmac_f32_e32 v65, v28, v38
	v_fmac_f32_e32 v25, v18, v38
	v_fmac_f32_e32 v65, v30, v39
	v_fmac_f32_e32 v25, v19, v39
	v_fmac_f32_e32 v65, v31, v46
	v_fmac_f32_e32 v25, v14, v46
	v_fmac_f32_e32 v65, v32, v47
	v_fmac_f32_e32 v25, v15, v47
	ds_read_b128 v[36:39], v29 offset:13184
	v_fmac_f32_e32 v65, v33, v48
	v_fmac_f32_e32 v25, v12, v48
	v_fmac_f32_e32 v65, v34, v49
	v_fmac_f32_e32 v25, v13, v49
	v_fmac_f32_e32 v65, v35, v60
	v_fmac_f32_e32 v25, v4, v60
	v_fmac_f32_e32 v65, v40, v61
	v_fmac_f32_e32 v25, v5, v61
	v_fmac_f32_e32 v65, v41, v62
	v_fmac_f32_e32 v25, v16, v62
	s_waitcnt lgkmcnt(0)
	v_fma_f32 v43, -v10, v36, v43
	v_fma_f32 v20, v22, v36, v20
	v_fmac_f32_e32 v65, v59, v63
	v_fmac_f32_e32 v25, v17, v63
	ds_read_b128 v[44:47], v29 offset:13200
	ds_read_b128 v[48:51], v29 offset:13216
	ds_read_b128 v[60:63], v29 offset:13232
	v_fmac_f32_e32 v43, v27, v37
	v_fmac_f32_e32 v20, v23, v37
	v_fmac_f32_e32 v43, v28, v38
	v_fmac_f32_e32 v20, v18, v38
	v_fmac_f32_e32 v43, v30, v39
	v_fmac_f32_e32 v20, v19, v39
	s_waitcnt lgkmcnt(2)
	v_fmac_f32_e32 v43, v31, v44
	v_fmac_f32_e32 v20, v14, v44
	v_fmac_f32_e32 v43, v32, v45
	v_fmac_f32_e32 v20, v15, v45
	v_fmac_f32_e32 v43, v33, v46
	v_fmac_f32_e32 v20, v12, v46
	v_fmac_f32_e32 v43, v34, v47
	v_fmac_f32_e32 v20, v13, v47
	ds_read_b128 v[36:39], v29 offset:13248
	s_waitcnt lgkmcnt(2)
	v_fmac_f32_e32 v43, v35, v48
	v_fmac_f32_e32 v20, v4, v48
	v_fmac_f32_e32 v43, v40, v49
	v_fmac_f32_e32 v20, v5, v49
	v_fmac_f32_e32 v43, v41, v50
	v_fmac_f32_e32 v20, v16, v50
	v_fmac_f32_e32 v43, v59, v51
	v_fmac_f32_e32 v20, v17, v51
	v_fmac_f32_e32 v65, v68, v64
	v_fmac_f32_e32 v25, v24, v64
	s_waitcnt lgkmcnt(1)
	v_fmac_f32_e32 v43, v68, v60
	v_fmac_f32_e32 v20, v24, v60
	s_waitcnt lgkmcnt(0)
; #define GAS __attribute__((address_space(1)))
; #define LAS __attribute__((address_space(3)))
; DI unsigned short cvt1(float x) { return (unsigned short)(cvtpk(x, 0.f) & 0xffffu); }
; #define CS_LWAIT() asm volatile("s_waitcnt lgkmcnt(0)" ::: "memory")
; DI void chunk_prep(const bf16* PROJ, const float* mu, const bf16* LO, const float* pw0, const float* pa0, const float* pkk, const float* pka, const float* prk, float* SCAL, unsigned char* OPS, float* G15, LAS unsigned char* lds, int gw, int NGW, int wave, int lane) {
;     ...
;     for (int task = gw; task < NTASK; task += NGW) {
;         const int chain = task / NCHUNK, c = task - chain * NCHUNK, bb = chain >> 3, hd = chain & 7;
;         const size_t m0 = (size_t)bb * SEQ + (size_t)c * 16;
;         float a[16], b[16], k[16], r[16]; float g = 1.f;
;         {
;             const int ch = hd * 64 + d;
;             const float w0v = ((const GAS float*)pw0)[ch], a0v = ((const GAS float*)pa0)[ch], kkv = ((const GAS float*)pkk)[ch], kav = ((const GAS float*)pka)[ch], rkv = ((const GAS float*)prk)[ch];
;             const float mur = ((const GAS float*)mu)[ch], muk = ((const GAS float*)mu)[512 + ch];
;             float w[16], wl[16], al[16];
;             { const GAS bf16* pj = (const GAS bf16*)PROJ + m0 * INP + (INC - RWC) + ch;
;               float pr_ = 0.f, pk_ = 0.f; if (c != 0) { pr_ = bf2f(*(pj - INP)); pk_ = bf2f(*(pj - INP + 512)); }
;     ...
;         CS_LWAIT();
; #pragma unroll
;         for (int t = 0; t < 16; ++t) { *(LAS unsigned short*)(base + L_AT + (t * 64 + d) * 2) = cvt1(a[t]); *(LAS float*)(base + L_AK + (t * 16 + x) * 4) = mm[t]; }
;         CS_LWAIT();
	v_fma_f32 v10, -v10, v36, v42
	v_fmac_f32_e32 v43, v65, v61
	v_fmac_f32_e32 v20, v25, v61
	ds_read_b128 v[44:47], v29 offset:13264
	ds_read_b128 v[48:51], v29 offset:13280
	ds_read_b128 v[60:63], v29 offset:13296
	v_fmac_f32_e32 v10, v27, v37
	s_waitcnt lgkmcnt(0)
	ds_write_b16 v1, v2
	v_cvt_pk_bf16_f32 v2, v27, s0
	v_fmac_f32_e32 v21, v22, v36
	v_fmac_f32_e32 v10, v28, v38
	ds_write_b16 v1, v2 offset:128
	ds_write2_b32 v26, v22, v23 offset1:16
	v_cvt_pk_bf16_f32 v2, v28, s0
	v_fmac_f32_e32 v21, v23, v37
	v_fmac_f32_e32 v10, v30, v39
	ds_write_b16 v1, v2 offset:256
	v_cvt_pk_bf16_f32 v2, v30, s0
	v_fmac_f32_e32 v21, v18, v38
	s_waitcnt lgkmcnt(6)
	v_fmac_f32_e32 v10, v31, v44
	ds_write_b16 v1, v2 offset:384
	ds_write2_b32 v26, v18, v19 offset0:32 offset1:48
	v_cvt_pk_bf16_f32 v2, v31, s0
	v_fmac_f32_e32 v21, v19, v39
	v_fmac_f32_e32 v10, v32, v45
	ds_write_b16 v1, v2 offset:512
	v_cvt_pk_bf16_f32 v2, v32, s0
	v_fmac_f32_e32 v21, v14, v44
	v_fmac_f32_e32 v10, v33, v46
	ds_write_b16 v1, v2 offset:640
	ds_write2_b32 v26, v14, v15 offset0:64 offset1:80
	v_cvt_pk_bf16_f32 v2, v33, s0
	v_fmac_f32_e32 v21, v15, v45
	v_fmac_f32_e32 v10, v34, v47
	ds_write_b16 v1, v2 offset:768
	v_cvt_pk_bf16_f32 v2, v34, s0
	v_fmac_f32_e32 v21, v12, v46
	s_waitcnt lgkmcnt(11)
	v_fmac_f32_e32 v10, v35, v48
	ds_write_b16 v1, v2 offset:896
	ds_write2_b32 v26, v12, v13 offset0:96 offset1:112
	v_cvt_pk_bf16_f32 v2, v35, s0
	v_fmac_f32_e32 v21, v13, v47
	v_fmac_f32_e32 v10, v40, v49
	ds_write_b16 v1, v2 offset:1024
	v_cvt_pk_bf16_f32 v2, v40, s0
	v_fmac_f32_e32 v21, v4, v48
	v_fmac_f32_e32 v10, v41, v50
	ds_write_b16 v1, v2 offset:1152
	ds_write2_b32 v26, v4, v5 offset0:128 offset1:144
	v_cvt_pk_bf16_f32 v2, v41, s0
	v_fmac_f32_e32 v21, v5, v49
	v_fmac_f32_e32 v10, v59, v51
	ds_write_b16 v1, v2 offset:1280
	v_cvt_pk_bf16_f32 v2, v59, s0
	v_fmac_f32_e32 v21, v16, v50
	s_waitcnt lgkmcnt(14)
	v_fmac_f32_e32 v10, v68, v60
	ds_write_b16 v1, v2 offset:1408
	ds_write2_b32 v26, v16, v17 offset0:160 offset1:176
	v_cvt_pk_bf16_f32 v2, v68, s0
	v_fmac_f32_e32 v21, v17, v51
	v_fmac_f32_e32 v10, v65, v61
	ds_write_b16 v1, v2 offset:1536
	v_cvt_pk_bf16_f32 v2, v65, s0
	v_fmac_f32_e32 v21, v24, v60
	v_fmac_f32_e32 v10, v43, v62
	ds_write_b16 v1, v2 offset:1664
	ds_write2_b32 v26, v24, v25 offset0:192 offset1:208
	v_cvt_pk_bf16_f32 v2, v43, s0
	v_fmac_f32_e32 v21, v25, v61
	ds_write_b16 v1, v2 offset:1792
	v_cvt_pk_bf16_f32 v2, v10, s0
	v_fmac_f32_e32 v21, v20, v62
	ds_write_b16 v1, v2 offset:1920
	ds_write2_b32 v26, v20, v21 offset0:224 offset1:240
	s_waitcnt lgkmcnt(0)
	v_mov_b32_e32 v250, v6
	v_mov_b32_e32 v251, v7
	v_lshl_add_u64 v[6:7], v[6:7], 0, s[34:35]
	s_mov_b32 s100, 1
	s_waitcnt lgkmcnt(0)
	s_cmp_lt_i32 s54, s101
	s_cbranch_scc1 .Lmy_cp_next
	s_cmp_eq_u32 s101, 0x4000
	s_cbranch_scc0 .LBB0_890
	s_sub_i32 s54, s54, 0xc00
	s_sub_u32 s38, s38, 0xc000
	s_subb_u32 s39, s39, 0
	s_mov_b32 s98, 0xfff40000
	s_mov_b32 s99, -1
	v_lshl_add_u64 v[8:9], v[8:9], 0, s[98:99]
	s_mov_b32 s98, 0xfe200000
	v_lshl_add_u64 v[6:7], v[6:7], 0, s[98:99]
	s_mov_b32 s101, 0
.Lmy_cp_next:
.LBB0_856:
	s_ashr_i32 s42, s54, 31
	s_lshr_b32 s42, s42, 23
	s_add_i32 s50, s54, s42
	s_bfe_u32 s42, s50, 0x30009
	v_lshl_or_b32 v2, s42, 6, v186
	v_lshlrev_b32_e32 v4, 2, v2
	s_waitcnt lgkmcnt(0)
	global_load_dword v59, v4, s[22:23]
	global_load_dword v90, v4, s[24:25]
	global_load_dword v88, v4, s[26:27]
	global_load_dword v23, v4, s[28:29]
	global_load_dword v87, v4, s[30:31]
	global_load_dword v74, v4, s[18:19]
	global_load_dword v22, v4, s[18:19] offset:2048
	s_and_b32 s56, s50, 0xfffffe00
	s_ashr_i32 s50, s50, 12
	s_ashr_i32 s51, s50, 31
	s_ashr_i32 s57, s56, 31
	s_lshl_b64 s[50:51], s[50:51], 13
	s_lshl_b64 s[58:59], s[56:57], 4
	s_sub_u32 s50, s50, s58
	s_subb_u32 s51, s51, s59
	s_add_u32 s50, s38, s50
	s_addc_u32 s51, s39, s51
	s_mul_i32 s55, s51, 0x1200
	s_mul_hi_u32 s57, s50, 0x1200
	s_add_i32 s57, s57, s55
	s_mul_i32 s55, s50, 0x1200
	s_add_u32 s58, s44, s55
	s_addc_u32 s59, s45, s57
	v_lshlrev_b32_e32 v2, 1, v2
	v_lshl_add_u64 v[4:5], s[58:59], 0, v[2:3]
	s_mov_b64 s[58:59], 0x2b400340
	v_lshl_add_u64 v[14:15], v[4:5], 0, s[58:59]
	s_cmp_eq_u32 s54, s56
	v_mov_b32_e32 v12, v3
	v_mov_b32_e32 v13, v3
	s_cbranch_scc1 .LBB0_858
	v_add_co_u32_e32 v4, vcc, 0xfffff000, v14
	s_nop 1
	v_addc_co_u32_e32 v5, vcc, -1, v15, vcc
	global_load_ushort v4, v[4:5], off offset:-512
	s_nop 0
	global_load_ushort v5, v[14:15], off offset:-3584
	s_waitcnt vmcnt(1)
	v_lshlrev_b32_e32 v13, 16, v4
	s_waitcnt vmcnt(0)
	v_lshlrev_b32_e32 v12, 16, v5
